# GEMM K-loop LDS-DMA loads use scalar base + 32-bit lane offset (no per-load 64-bit VALU address adds), plus unit-drain removal
# speedup vs baseline: 1.0356x; 1.0049x over previous
; #define PG8_STAGE(bufoff, gbase, voff) do { _Pragma("unroll") for (int _i = 0; _i < 2; ++_i) \
;         __builtin_amdgcn_global_load_lds((const unsigned*)((const char*)(gbase) + (voff)[_i]), (PG8_LAS unsigned*)(lds + (bufoff) + ldsw + _i * 8192), 16, 0, 0); } while (0)
; #define PG8_LDA(dst, b, h) do { _Pragma("unroll") for (int m = 0; m < 4; ++m) _Pragma("unroll") for (int k = 0; k < 2; ++k) dst[m][k] = *(const PG8_LAS bf16x8*)(lds + PG8_SA(b, h) + aoff + m * 2048 + k * 1024); } while (0)
; #define PG8_LDB(dst, b, h) do { _Pragma("unroll") for (int n = 0; n < 2; ++n) _Pragma("unroll") for (int k = 0; k < 2; ++k) dst[n][k] = *(const PG8_LAS bf16x8*)(lds + PG8_SB(b, h) + boff + n * 2048 + k * 1024); } while (0)
; #define PG8_MMA(ai, bj, At, Bt) do { __builtin_amdgcn_s_setprio(1); _Pragma("unroll") for (int m = 0; m < 4; ++m) _Pragma("unroll") for (int n = 0; n < 2; ++n) _Pragma("unroll") for (int k = 0; k < 2; ++k) \
;         acc[ai][bj][m][n] = __builtin_amdgcn_mfma_f32_16x16x32_bf16(Bt[n][k], At[m][k], acc[ai][bj][m][n], 0, 0, 0); __builtin_amdgcn_s_setprio(0); } while (0)
; #define PG8_WAIT_V(n) asm volatile("s_waitcnt vmcnt(" #n ")" ::: "memory")
; #define PG8_WAIT_L(n) asm volatile("s_waitcnt lgkmcnt(" #n ")" ::: "memory")
; #define PG8_BAR __builtin_amdgcn_s_barrier()
; #define PG8_SCHED __builtin_amdgcn_sched_barrier(0)
; template <class Epi, class Sched, bool ALIGN_EPI = false, bool SP2 = false>
; __device__ __forceinline__ void gemm_phase(PG8_LAS unsigned char* lds, const Gemm g, const Sched& S, const Epi& E, const int tid_in) {
;     ...
;             PG8_LDB(B0, 0, 0); PG8_LDB(B1, 0, 1); PG8_SCHED; PG8_LDA(At, 0, 0); PG8_STAGE(PG8_SA(1, 1), a1 + hstep, voffA);
;             PG8_WAIT_V(8); PG8_WAIT_L(0); PG8_BAR; PG8_MMA(0, 0, At, B0); PG8_MMA(0, 1, At, B1); PG8_BAR; PG8_SCHED;
;             PG8_LDA(At, 0, 1); PG8_STAGE(PG8_SB(0, 0), b2, voffB); PG8_STAGE(PG8_SB(0, 1), b2 + hstep, voffB); PG8_STAGE(PG8_SA(0, 0), a2, voffA);
;             PG8_WAIT_V(8); PG8_WAIT_L(0); PG8_BAR; PG8_MMA(1, 0, At, B0); PG8_MMA(1, 1, At, B1); PG8_BAR; PG8_SCHED;
.LBB0_115:
	s_add_i32 s77, s52, 2
	s_add_u32 vcc_lo, s2, s10
	s_addc_u32 s53, s3, s11
	s_add_u32 s44, s50, s10
	s_addc_u32 s45, s51, s11
	s_add_i32 s16, 0, 0x10000
	s_cmp_eq_u32 s68, s52
	s_cselect_b32 s53, s49, s53
	s_cselect_b32 s52, s48, vcc_lo
	v_add_u32_e32 v0, s16, v177
	s_cselect_b32 vcc_hi, s43, s45
	s_cselect_b32 vcc_lo, s42, s44
	s_add_i32 s17, 0, 0x14000
	ds_read_b128 v[134:137], v0
	ds_read_b128 v[138:141], v0 offset:1024
	ds_read_b128 v[142:145], v0 offset:2048
	ds_read_b128 v[146:149], v0 offset:3072
	v_add_u32_e32 v0, s17, v177
	ds_read_b128 v[150:153], v0
	ds_read_b128 v[154:157], v0 offset:1024
	ds_read_b128 v[158:161], v0 offset:2048
	ds_read_b128 v[180:183], v0 offset:3072
	s_add_i32 m0, s60, 0xc000
	ds_read_b128 v[184:187], v179
	ds_read_b128 v[188:191], v179 offset:1024
	ds_read_b128 v[192:195], v179 offset:2048
	ds_read_b128 v[196:199], v179 offset:3072
	ds_read_b128 v[200:203], v179 offset:4096
	ds_read_b128 v[204:207], v179 offset:5120
	ds_read_b128 v[208:211], v179 offset:6144
	ds_read_b128 v[212:215], v179 offset:7168
	global_load_lds_dwordx4 v132, s[2:3]
	s_add_i32 m0, s60, 0xe000
	s_nop 0
	global_load_lds_dwordx4 v130, s[2:3]
	s_waitcnt vmcnt(8)
	s_waitcnt lgkmcnt(0)
	s_barrier
	s_setprio 1
	s_waitcnt lgkmcnt(0)
	v_mfma_f32_16x16x32_bf16 v[126:129], v[134:137], v[184:187], v[126:129]
	v_mfma_f32_16x16x32_bf16 v[122:125], v[142:145], v[184:187], v[122:125]
	v_mfma_f32_16x16x32_bf16 v[110:113], v[134:137], v[192:195], v[110:113]
	v_mfma_f32_16x16x32_bf16 v[106:109], v[142:145], v[192:195], v[106:109]
	v_mfma_f32_16x16x32_bf16 v[94:97], v[134:137], v[200:203], v[94:97]
	v_mfma_f32_16x16x32_bf16 v[90:93], v[142:145], v[200:203], v[90:93]
	v_mfma_f32_16x16x32_bf16 v[78:81], v[134:137], v[208:211], v[78:81]
	v_mfma_f32_16x16x32_bf16 v[74:77], v[142:145], v[208:211], v[74:77]
	v_mfma_f32_16x16x32_bf16 v[126:129], v[138:141], v[188:191], v[126:129]
	v_mfma_f32_16x16x32_bf16 v[122:125], v[146:149], v[188:191], v[122:125]
	v_mfma_f32_16x16x32_bf16 v[110:113], v[138:141], v[196:199], v[110:113]
	v_mfma_f32_16x16x32_bf16 v[106:109], v[146:149], v[196:199], v[106:109]
	v_mfma_f32_16x16x32_bf16 v[94:97], v[138:141], v[204:207], v[94:97]
	v_mfma_f32_16x16x32_bf16 v[90:93], v[146:149], v[204:207], v[90:93]
	v_mfma_f32_16x16x32_bf16 v[78:81], v[138:141], v[212:215], v[78:81]
	v_mfma_f32_16x16x32_bf16 v[74:77], v[146:149], v[212:215], v[74:77]
	s_setprio 0
	s_setprio 1
	v_mfma_f32_16x16x32_bf16 v[118:121], v[150:153], v[184:187], v[118:121]
	v_mfma_f32_16x16x32_bf16 v[114:117], v[158:161], v[184:187], v[114:117]
	v_mfma_f32_16x16x32_bf16 v[102:105], v[150:153], v[192:195], v[102:105]
	v_mfma_f32_16x16x32_bf16 v[98:101], v[158:161], v[192:195], v[98:101]
	v_mfma_f32_16x16x32_bf16 v[86:89], v[150:153], v[200:203], v[86:89]
	v_mfma_f32_16x16x32_bf16 v[82:85], v[158:161], v[200:203], v[82:85]
	v_mfma_f32_16x16x32_bf16 v[70:73], v[150:153], v[208:211], v[70:73]
	v_mfma_f32_16x16x32_bf16 v[66:69], v[158:161], v[208:211], v[66:69]
	v_mfma_f32_16x16x32_bf16 v[118:121], v[154:157], v[188:191], v[118:121]
	v_mfma_f32_16x16x32_bf16 v[114:117], v[180:183], v[188:191], v[114:117]
	v_mfma_f32_16x16x32_bf16 v[102:105], v[154:157], v[196:199], v[102:105]
	v_mfma_f32_16x16x32_bf16 v[98:101], v[180:183], v[196:199], v[98:101]
	v_mfma_f32_16x16x32_bf16 v[86:89], v[154:157], v[204:207], v[86:89]
	v_mfma_f32_16x16x32_bf16 v[82:85], v[180:183], v[204:207], v[82:85]
	v_mfma_f32_16x16x32_bf16 v[70:73], v[154:157], v[212:215], v[70:73]
	v_mfma_f32_16x16x32_bf16 v[66:69], v[180:183], v[212:215], v[66:69]
	s_setprio 0
	s_barrier
	s_add_i32 s16, s16, s59
	s_add_u32 s98, vcc_lo, 0x80
	s_addc_u32 s99, vcc_hi, 0
	s_add_u32 s100, s52, 0x80
	s_addc_u32 s101, s53, 0
	s_mov_b32 m0, s16
	ds_read_b128 v[184:187], v179 offset:16384
	ds_read_b128 v[188:191], v179 offset:17408
	ds_read_b128 v[192:195], v179 offset:18432
	ds_read_b128 v[196:199], v179 offset:19456
	ds_read_b128 v[200:203], v179 offset:20480
	ds_read_b128 v[204:207], v179 offset:21504
	ds_read_b128 v[208:211], v179 offset:22528
	ds_read_b128 v[212:215], v179 offset:23552
	global_load_lds_dwordx4 v164, vcc
	s_add_i32 m0, s16, 0x2000
	s_add_i32 s16, s17, s59
	global_load_lds_dwordx4 v168, vcc
	s_add_u32 vcc_lo, vcc_lo, s82
	s_addc_u32 vcc_hi, vcc_hi, 0
	s_mov_b32 m0, s16
	s_nop 0
	global_load_lds_dwordx4 v164, vcc
	s_add_i32 m0, s16, 0x2000
	s_nop 0
	global_load_lds_dwordx4 v168, vcc
	s_mov_b32 m0, s60
	s_nop 0
	global_load_lds_dwordx4 v162, s[52:53]
	s_mov_b32 m0, s61
	s_nop 0
	global_load_lds_dwordx4 v166, s[52:53]
	s_waitcnt vmcnt(8)
	s_waitcnt lgkmcnt(0)
	s_barrier
; #define PG8_STAGE(bufoff, gbase, voff) do { _Pragma("unroll") for (int _i = 0; _i < 2; ++_i) \
;         __builtin_amdgcn_global_load_lds((const unsigned*)((const char*)(gbase) + (voff)[_i]), (PG8_LAS unsigned*)(lds + (bufoff) + ldsw + _i * 8192), 16, 0, 0); } while (0)
; #define PG8_LDA(dst, b, h) do { _Pragma("unroll") for (int m = 0; m < 4; ++m) _Pragma("unroll") for (int k = 0; k < 2; ++k) dst[m][k] = *(const PG8_LAS bf16x8*)(lds + PG8_SA(b, h) + aoff + m * 2048 + k * 1024); } while (0)
; #define PG8_LDB(dst, b, h) do { _Pragma("unroll") for (int n = 0; n < 2; ++n) _Pragma("unroll") for (int k = 0; k < 2; ++k) dst[n][k] = *(const PG8_LAS bf16x8*)(lds + PG8_SB(b, h) + boff + n * 2048 + k * 1024); } while (0)
; #define PG8_MMA(ai, bj, At, Bt) do { __builtin_amdgcn_s_setprio(1); _Pragma("unroll") for (int m = 0; m < 4; ++m) _Pragma("unroll") for (int n = 0; n < 2; ++n) _Pragma("unroll") for (int k = 0; k < 2; ++k) \
;         acc[ai][bj][m][n] = __builtin_amdgcn_mfma_f32_16x16x32_bf16(Bt[n][k], At[m][k], acc[ai][bj][m][n], 0, 0, 0); __builtin_amdgcn_s_setprio(0); } while (0)
; #define PG8_WAIT_V(n) asm volatile("s_waitcnt vmcnt(" #n ")" ::: "memory")
; #define PG8_WAIT_L(n) asm volatile("s_waitcnt lgkmcnt(" #n ")" ::: "memory")
; #define PG8_BAR __builtin_amdgcn_s_barrier()
; #define PG8_SCHED __builtin_amdgcn_sched_barrier(0)
; template <class Epi, class Sched, bool ALIGN_EPI = false, bool SP2 = false>
; __device__ __forceinline__ void gemm_phase(PG8_LAS unsigned char* lds, const Gemm g, const Sched& S, const Epi& E, const int tid_in) {
;     ...
;             PG8_WAIT_V(8); PG8_WAIT_L(0); PG8_BAR; PG8_MMA(1, 0, At, B0); PG8_MMA(1, 1, At, B1); PG8_BAR; PG8_SCHED;
;             PG8_LDB(B0, 1, 0); PG8_LDB(B1, 1, 1); PG8_SCHED; PG8_LDA(At, 1, 0); PG8_STAGE(PG8_SA(0, 1), a2 + hstep, voffA);
;             PG8_WAIT_V(8); PG8_WAIT_L(0); PG8_BAR; PG8_MMA(0, 0, At, B0); PG8_MMA(0, 1, At, B1); PG8_BAR; PG8_SCHED;
	s_setprio 1
	s_waitcnt lgkmcnt(0)
	v_mfma_f32_16x16x32_bf16 v[62:65], v[134:137], v[184:187], v[62:65]
	v_mfma_f32_16x16x32_bf16 v[58:61], v[142:145], v[184:187], v[58:61]
	v_mfma_f32_16x16x32_bf16 v[46:49], v[134:137], v[192:195], v[46:49]
	v_mfma_f32_16x16x32_bf16 v[42:45], v[142:145], v[192:195], v[42:45]
	v_mfma_f32_16x16x32_bf16 v[30:33], v[134:137], v[200:203], v[30:33]
	v_mfma_f32_16x16x32_bf16 v[26:29], v[142:145], v[200:203], v[26:29]
	v_mfma_f32_16x16x32_bf16 v[14:17], v[134:137], v[208:211], v[14:17]
	v_mfma_f32_16x16x32_bf16 v[10:13], v[142:145], v[208:211], v[10:13]
	v_mfma_f32_16x16x32_bf16 v[62:65], v[138:141], v[188:191], v[62:65]
	v_mfma_f32_16x16x32_bf16 v[58:61], v[146:149], v[188:191], v[58:61]
	v_mfma_f32_16x16x32_bf16 v[46:49], v[138:141], v[196:199], v[46:49]
	v_mfma_f32_16x16x32_bf16 v[42:45], v[146:149], v[196:199], v[42:45]
	v_mfma_f32_16x16x32_bf16 v[30:33], v[138:141], v[204:207], v[30:33]
	v_mfma_f32_16x16x32_bf16 v[26:29], v[146:149], v[204:207], v[26:29]
	v_mfma_f32_16x16x32_bf16 v[14:17], v[138:141], v[212:215], v[14:17]
	v_mfma_f32_16x16x32_bf16 v[10:13], v[146:149], v[212:215], v[10:13]
	s_setprio 0
	s_setprio 1
	v_mfma_f32_16x16x32_bf16 v[54:57], v[150:153], v[184:187], v[54:57]
	v_mfma_f32_16x16x32_bf16 v[50:53], v[158:161], v[184:187], v[50:53]
	v_mfma_f32_16x16x32_bf16 v[38:41], v[150:153], v[192:195], v[38:41]
	v_mfma_f32_16x16x32_bf16 v[34:37], v[158:161], v[192:195], v[34:37]
	v_mfma_f32_16x16x32_bf16 v[22:25], v[150:153], v[200:203], v[22:25]
	v_mfma_f32_16x16x32_bf16 v[18:21], v[158:161], v[200:203], v[18:21]
	v_mfma_f32_16x16x32_bf16 v[6:9], v[150:153], v[208:211], v[6:9]
	v_mfma_f32_16x16x32_bf16 v[2:5], v[158:161], v[208:211], v[2:5]
	v_mfma_f32_16x16x32_bf16 v[54:57], v[154:157], v[188:191], v[54:57]
	v_mfma_f32_16x16x32_bf16 v[50:53], v[180:183], v[188:191], v[50:53]
	v_mfma_f32_16x16x32_bf16 v[38:41], v[154:157], v[196:199], v[38:41]
	v_mfma_f32_16x16x32_bf16 v[34:37], v[180:183], v[196:199], v[34:37]
	v_mfma_f32_16x16x32_bf16 v[22:25], v[154:157], v[204:207], v[22:25]
	v_mfma_f32_16x16x32_bf16 v[18:21], v[180:183], v[204:207], v[18:21]
	v_mfma_f32_16x16x32_bf16 v[6:9], v[154:157], v[212:215], v[6:9]
	v_mfma_f32_16x16x32_bf16 v[2:5], v[180:183], v[212:215], v[2:5]
	s_setprio 0
	s_barrier
	s_add_i32 s16, 0, 0x18000
	v_add_u32_e32 v0, s16, v177
	s_add_i32 s17, 0, 0x1c000
	ds_read_b128 v[134:137], v0
	ds_read_b128 v[138:141], v0 offset:1024
	ds_read_b128 v[142:145], v0 offset:2048
	ds_read_b128 v[146:149], v0 offset:3072
	v_add_u32_e32 v0, s17, v177
	ds_read_b128 v[150:153], v0
	ds_read_b128 v[154:157], v0 offset:1024
	ds_read_b128 v[158:161], v0 offset:2048
	ds_read_b128 v[180:183], v0 offset:3072
	s_add_u32 s52, s52, s82
	s_addc_u32 s53, s53, 0
	s_mov_b32 m0, s62
	ds_read_b128 v[184:187], v179 offset:32768
	ds_read_b128 v[188:191], v179 offset:33792
	ds_read_b128 v[192:195], v179 offset:34816
	ds_read_b128 v[196:199], v179 offset:35840
	ds_read_b128 v[200:203], v179 offset:36864
	ds_read_b128 v[204:207], v179 offset:37888
	ds_read_b128 v[208:211], v179 offset:38912
	ds_read_b128 v[212:215], v179 offset:39936
	global_load_lds_dwordx4 v162, s[52:53]
	s_mov_b32 m0, s63
	s_nop 0
	global_load_lds_dwordx4 v166, s[52:53]
	s_waitcnt vmcnt(8)
	s_waitcnt lgkmcnt(0)
	s_barrier
	s_setprio 1
	s_waitcnt lgkmcnt(0)
	v_mfma_f32_16x16x32_bf16 v[126:129], v[134:137], v[184:187], v[126:129]
	v_mfma_f32_16x16x32_bf16 v[122:125], v[142:145], v[184:187], v[122:125]
	v_mfma_f32_16x16x32_bf16 v[110:113], v[134:137], v[192:195], v[110:113]
	v_mfma_f32_16x16x32_bf16 v[106:109], v[142:145], v[192:195], v[106:109]
	v_mfma_f32_16x16x32_bf16 v[94:97], v[134:137], v[200:203], v[94:97]
	v_mfma_f32_16x16x32_bf16 v[90:93], v[142:145], v[200:203], v[90:93]
	v_mfma_f32_16x16x32_bf16 v[78:81], v[134:137], v[208:211], v[78:81]
	v_mfma_f32_16x16x32_bf16 v[74:77], v[142:145], v[208:211], v[74:77]
	v_mfma_f32_16x16x32_bf16 v[126:129], v[138:141], v[188:191], v[126:129]
	v_mfma_f32_16x16x32_bf16 v[122:125], v[146:149], v[188:191], v[122:125]
	v_mfma_f32_16x16x32_bf16 v[110:113], v[138:141], v[196:199], v[110:113]
	v_mfma_f32_16x16x32_bf16 v[106:109], v[146:149], v[196:199], v[106:109]
	v_mfma_f32_16x16x32_bf16 v[94:97], v[138:141], v[204:207], v[94:97]
	v_mfma_f32_16x16x32_bf16 v[90:93], v[146:149], v[204:207], v[90:93]
	v_mfma_f32_16x16x32_bf16 v[78:81], v[138:141], v[212:215], v[78:81]
	v_mfma_f32_16x16x32_bf16 v[74:77], v[146:149], v[212:215], v[74:77]
	s_setprio 0
	s_setprio 1
	v_mfma_f32_16x16x32_bf16 v[118:121], v[150:153], v[184:187], v[118:121]
	v_mfma_f32_16x16x32_bf16 v[114:117], v[158:161], v[184:187], v[114:117]
	v_mfma_f32_16x16x32_bf16 v[102:105], v[150:153], v[192:195], v[102:105]
	v_mfma_f32_16x16x32_bf16 v[98:101], v[158:161], v[192:195], v[98:101]
	v_mfma_f32_16x16x32_bf16 v[86:89], v[150:153], v[200:203], v[86:89]
	v_mfma_f32_16x16x32_bf16 v[82:85], v[158:161], v[200:203], v[82:85]
	v_mfma_f32_16x16x32_bf16 v[70:73], v[150:153], v[208:211], v[70:73]
	v_mfma_f32_16x16x32_bf16 v[66:69], v[158:161], v[208:211], v[66:69]
	v_mfma_f32_16x16x32_bf16 v[118:121], v[154:157], v[188:191], v[118:121]
	v_mfma_f32_16x16x32_bf16 v[114:117], v[180:183], v[188:191], v[114:117]
	v_mfma_f32_16x16x32_bf16 v[102:105], v[154:157], v[196:199], v[102:105]
	v_mfma_f32_16x16x32_bf16 v[98:101], v[180:183], v[196:199], v[98:101]
	v_mfma_f32_16x16x32_bf16 v[86:89], v[154:157], v[204:207], v[86:89]
	v_mfma_f32_16x16x32_bf16 v[82:85], v[180:183], v[204:207], v[82:85]
	v_mfma_f32_16x16x32_bf16 v[70:73], v[154:157], v[212:215], v[70:73]
	v_mfma_f32_16x16x32_bf16 v[66:69], v[180:183], v[212:215], v[66:69]
	s_setprio 0
	s_barrier
; #define PG8_STAGE(bufoff, gbase, voff) do { _Pragma("unroll") for (int _i = 0; _i < 2; ++_i) \
;         __builtin_amdgcn_global_load_lds((const unsigned*)((const char*)(gbase) + (voff)[_i]), (PG8_LAS unsigned*)(lds + (bufoff) + ldsw + _i * 8192), 16, 0, 0); } while (0)
; #define PG8_LDA(dst, b, h) do { _Pragma("unroll") for (int m = 0; m < 4; ++m) _Pragma("unroll") for (int k = 0; k < 2; ++k) dst[m][k] = *(const PG8_LAS bf16x8*)(lds + PG8_SA(b, h) + aoff + m * 2048 + k * 1024); } while (0)
; #define PG8_MMA(ai, bj, At, Bt) do { __builtin_amdgcn_s_setprio(1); _Pragma("unroll") for (int m = 0; m < 4; ++m) _Pragma("unroll") for (int n = 0; n < 2; ++n) _Pragma("unroll") for (int k = 0; k < 2; ++k) \
;         acc[ai][bj][m][n] = __builtin_amdgcn_mfma_f32_16x16x32_bf16(Bt[n][k], At[m][k], acc[ai][bj][m][n], 0, 0, 0); __builtin_amdgcn_s_setprio(0); } while (0)
; #define PG8_WAIT_V(n) asm volatile("s_waitcnt vmcnt(" #n ")" ::: "memory")
; #define PG8_WAIT_L(n) asm volatile("s_waitcnt lgkmcnt(" #n ")" ::: "memory")
; #define PG8_BAR __builtin_amdgcn_s_barrier()
; #define PG8_SCHED __builtin_amdgcn_sched_barrier(0)
; template <class Epi, class Sched, bool ALIGN_EPI = false, bool SP2 = false>
; __device__ __forceinline__ void gemm_phase(PG8_LAS unsigned char* lds, const Gemm g, const Sched& S, const Epi& E, const int tid_in) {
;     ...
;         for (int t = 0; t < nt; t += 2) {
;             const bool last = (t == nt - 2);
;             const char* a1 = cA + (size_t)(t + 1) * kstep;
;             const char* a2 = last ? nA : cA + (size_t)(t + 2) * kstep; const char* b2 = last ? nB : cB + (size_t)(t + 2) * kstep;
;             const char* a3 = a2 + kstep; const char* b3 = b2 + kstep;
;     ...
;             PG8_LDA(At, 1, 1); PG8_STAGE(PG8_SB(1, 0), b3, voffB); PG8_STAGE(PG8_SB(1, 1), b3 + hstep, voffB); PG8_STAGE(PG8_SA(1, 0), a3, voffA);
;             PG8_WAIT_V(8); PG8_WAIT_L(0); PG8_BAR; PG8_MMA(1, 0, At, B0); PG8_MMA(1, 1, At, B1); PG8_BAR; PG8_SCHED;
	s_add_i32 s16, s16, s59
	s_mov_b32 m0, s16
	ds_read_b128 v[184:187], v179 offset:49152
	ds_read_b128 v[188:191], v179 offset:50176
	ds_read_b128 v[192:195], v179 offset:51200
	ds_read_b128 v[196:199], v179 offset:52224
	ds_read_b128 v[200:203], v179 offset:53248
	ds_read_b128 v[204:207], v179 offset:54272
	ds_read_b128 v[208:211], v179 offset:55296
	ds_read_b128 v[212:215], v179 offset:56320
	global_load_lds_dwordx4 v164, s[98:99]
	s_add_i32 m0, s16, 0x2000
	s_add_i32 s16, s17, s59
	global_load_lds_dwordx4 v168, s[98:99]
	s_add_u32 vcc_lo, vcc_lo, 0x80
	s_addc_u32 vcc_hi, vcc_hi, 0
	s_mov_b32 m0, s16
	s_nop 0
	global_load_lds_dwordx4 v164, vcc
	s_add_i32 m0, s16, 0x2000
	s_nop 0
	global_load_lds_dwordx4 v168, vcc
	s_mov_b32 m0, s66
	s_nop 0
	global_load_lds_dwordx4 v162, s[100:101]
	s_mov_b32 m0, s67
	s_nop 0
	global_load_lds_dwordx4 v166, s[100:101]
	s_waitcnt vmcnt(8)
	s_waitcnt lgkmcnt(0)
	s_barrier
	s_setprio 1
	s_waitcnt lgkmcnt(0)
	v_mfma_f32_16x16x32_bf16 v[62:65], v[134:137], v[184:187], v[62:65]
	v_mfma_f32_16x16x32_bf16 v[58:61], v[142:145], v[184:187], v[58:61]
	v_mfma_f32_16x16x32_bf16 v[46:49], v[134:137], v[192:195], v[46:49]
	v_mfma_f32_16x16x32_bf16 v[42:45], v[142:145], v[192:195], v[42:45]
	v_mfma_f32_16x16x32_bf16 v[30:33], v[134:137], v[200:203], v[30:33]
	v_mfma_f32_16x16x32_bf16 v[26:29], v[142:145], v[200:203], v[26:29]
	v_mfma_f32_16x16x32_bf16 v[14:17], v[134:137], v[208:211], v[14:17]
	v_mfma_f32_16x16x32_bf16 v[10:13], v[142:145], v[208:211], v[10:13]
	v_mfma_f32_16x16x32_bf16 v[62:65], v[138:141], v[188:191], v[62:65]
	v_mfma_f32_16x16x32_bf16 v[58:61], v[146:149], v[188:191], v[58:61]
	v_mfma_f32_16x16x32_bf16 v[46:49], v[138:141], v[196:199], v[46:49]
	v_mfma_f32_16x16x32_bf16 v[42:45], v[146:149], v[196:199], v[42:45]
	v_mfma_f32_16x16x32_bf16 v[30:33], v[138:141], v[204:207], v[30:33]
	v_mfma_f32_16x16x32_bf16 v[26:29], v[146:149], v[204:207], v[26:29]
	v_mfma_f32_16x16x32_bf16 v[14:17], v[138:141], v[212:215], v[14:17]
	v_mfma_f32_16x16x32_bf16 v[10:13], v[146:149], v[212:215], v[10:13]
	s_setprio 0
	s_setprio 1
	v_mfma_f32_16x16x32_bf16 v[54:57], v[150:153], v[184:187], v[54:57]
	v_mfma_f32_16x16x32_bf16 v[50:53], v[158:161], v[184:187], v[50:53]
	v_mfma_f32_16x16x32_bf16 v[38:41], v[150:153], v[192:195], v[38:41]
	v_mfma_f32_16x16x32_bf16 v[34:37], v[158:161], v[192:195], v[34:37]
	v_mfma_f32_16x16x32_bf16 v[22:25], v[150:153], v[200:203], v[22:25]
	v_mfma_f32_16x16x32_bf16 v[18:21], v[158:161], v[200:203], v[18:21]
	v_mfma_f32_16x16x32_bf16 v[6:9], v[150:153], v[208:211], v[6:9]
	v_mfma_f32_16x16x32_bf16 v[2:5], v[158:161], v[208:211], v[2:5]
	v_mfma_f32_16x16x32_bf16 v[54:57], v[154:157], v[188:191], v[54:57]
	v_mfma_f32_16x16x32_bf16 v[50:53], v[180:183], v[188:191], v[50:53]
	v_mfma_f32_16x16x32_bf16 v[38:41], v[154:157], v[196:199], v[38:41]
	v_mfma_f32_16x16x32_bf16 v[34:37], v[180:183], v[196:199], v[34:37]
	v_mfma_f32_16x16x32_bf16 v[22:25], v[154:157], v[204:207], v[22:25]
	v_mfma_f32_16x16x32_bf16 v[18:21], v[180:183], v[204:207], v[18:21]
	v_mfma_f32_16x16x32_bf16 v[6:9], v[154:157], v[212:215], v[6:9]
	v_mfma_f32_16x16x32_bf16 v[2:5], v[180:183], v[212:215], v[2:5]
	s_setprio 0
	s_barrier
	s_add_u32 s10, s10, 0x100
	s_addc_u32 s11, s11, 0
	v_lshl_add_u64 v[132:133], v[132:133], 0, s[88:89]
	v_lshl_add_u64 v[130:131], v[130:131], 0, s[88:89]
	s_cmp_ge_u32 s77, s65
	s_mov_b32 s52, s77
	s_cbranch_scc0 .LBB0_115
	s_and_b64 vcc, exec, s[46:47]
	s_cbranch_vccz .LBB0_118
	s_barrier

; __global__ void __launch_bounds__(NTHREADS, 2) fwd_megakernel(Params p_) {
	.amdhsa_kernel _Z14fwd_megakernel6Params
		.amdhsa_group_segment_fixed_size 0
		.amdhsa_private_segment_fixed_size 0
		.amdhsa_kernarg_size 544
		.amdhsa_user_sgpr_count 2
		.amdhsa_user_sgpr_dispatch_ptr 0
		.amdhsa_user_sgpr_queue_ptr 0
		.amdhsa_user_sgpr_kernarg_segment_ptr 1
		.amdhsa_user_sgpr_dispatch_id 0
		.amdhsa_user_sgpr_kernarg_preload_length 0
		.amdhsa_user_sgpr_kernarg_preload_offset 0
		.amdhsa_user_sgpr_private_segment_size 0
		.amdhsa_uses_dynamic_stack 0
		.amdhsa_enable_private_segment 0
		.amdhsa_system_sgpr_workgroup_id_x 1
		.amdhsa_system_sgpr_workgroup_id_y 0
		.amdhsa_system_sgpr_workgroup_id_z 0
		.amdhsa_system_sgpr_workgroup_info 0
		.amdhsa_system_vgpr_workitem_id 2
		.amdhsa_next_free_vgpr 256
		.amdhsa_next_free_sgpr 102
		.amdhsa_accum_offset 256
		.amdhsa_reserve_vcc 1
		.amdhsa_float_round_mode_32 0
		.amdhsa_float_round_mode_16_64 0
		.amdhsa_float_denorm_mode_32 3
		.amdhsa_float_denorm_mode_16_64 3
		.amdhsa_dx10_clamp 1
		.amdhsa_ieee_mode 1
		.amdhsa_fp16_overflow 0
		.amdhsa_tg_split 0
		.amdhsa_exception_fp_ieee_invalid_op 0
		.amdhsa_exception_fp_denorm_src 0
		.amdhsa_exception_fp_ieee_div_zero 0
		.amdhsa_exception_fp_ieee_overflow 0
		.amdhsa_exception_fp_ieee_underflow 0
		.amdhsa_exception_fp_ieee_inexact 0
		.amdhsa_exception_int_div_zero 0
	.end_amdhsa_kernel

; __global__ void __launch_bounds__(NTHREADS, 2) fwd_megakernel(Params p_) {
amdhsa.kernels:
  - .agpr_count:     0
    .args:
      - .offset:         0
        .size:           288
        .value_kind:     by_value
      - .offset:         288
        .size:           4
        .value_kind:     hidden_block_count_x
      - .offset:         292
        .size:           4
        .value_kind:     hidden_block_count_y
      - .offset:         296
        .size:           4
        .value_kind:     hidden_block_count_z
      - .offset:         300
        .size:           2
        .value_kind:     hidden_group_size_x
      - .offset:         302
        .size:           2
        .value_kind:     hidden_group_size_y
      - .offset:         304
        .size:           2
        .value_kind:     hidden_group_size_z
      - .offset:         306
        .size:           2
        .value_kind:     hidden_remainder_x
      - .offset:         308
        .size:           2
        .value_kind:     hidden_remainder_y
      - .offset:         310
        .size:           2
        .value_kind:     hidden_remainder_z
      - .offset:         328
        .size:           8
        .value_kind:     hidden_global_offset_x
      - .offset:         336
        .size:           8
        .value_kind:     hidden_global_offset_y
      - .offset:         344
        .size:           8
        .value_kind:     hidden_global_offset_z
      - .offset:         352
        .size:           2
        .value_kind:     hidden_grid_dims
      - .offset:         376
        .size:           8
        .value_kind:     hidden_multigrid_sync_arg
      - .offset:         408
        .size:           4
        .value_kind:     hidden_dynamic_lds_size
    .group_segment_fixed_size: 0
    .kernarg_segment_align: 8
    .kernarg_segment_size: 544
    .language:       OpenCL C
    .language_version:
      - 2
      - 0
    .max_flat_workgroup_size: 512
    .name:           _Z14fwd_megakernel6Params
    .private_segment_fixed_size: 0
    .sgpr_count:     108
    .sgpr_spill_count: 107
    .symbol:         _Z14fwd_megakernel6Params.kd
    .uniform_work_group_size: 1
    .uses_dynamic_stack: false
    .vgpr_count:     256
    .vgpr_spill_count: 0
    .wavefront_size: 64
